# speedup vs baseline: 1.0036x; 1.0036x over previous
; __device__ __forceinline__ u32 pack2(float a, float b) { return (u32)f2bf(a) | ((u32)f2bf(b) << 16); }
; __device__ __forceinline__ void phase0_misc(unsigned char* ws, int wv_) {
;     ...
;   {
;     const float4* src = (const float4*)inp(ws, 1);
;     uint2* dst = (uint2*)(ws + OFF_PB);
;     for (int i = gtid; i < 2 * T_ * 256 / 4; i += gsz) {
;       float4 v = src[i];
;       dst[i] = make_uint2(pack2(v.x, v.y), pack2(v.z, v.w));
;     }
;   }
.LBB0_26:
	s_or_b64 exec, exec, s[8:9]
	s_mov_b32 s6, 0x100000
	v_cmp_gt_i32_e32 vcc, s6, v6
	s_and_saveexec_b64 s[6:7], vcc
	s_cbranch_execz .LBB0_29
	s_load_dwordx2 s[10:11], s[0:1], 0x8
	v_readlane_b32 s8, v251, 7
	v_ashrrev_i32_e32 v9, 31, v8
	v_readlane_b32 s9, v251, 8
	s_mov_b32 s16, s8
	s_ashr_i32 s17, s8, 31
	v_writelane_b32 v251, s8, 7
	v_lshl_add_u64 v[4:5], v[8:9], 0, s[16:17]
	v_lshl_add_u64 v[2:3], v[4:5], 3, s[78:79]
	v_writelane_b32 v251, s9, 8
	s_mov_b64 s[8:9], 0x1c140000
	s_ashr_i32 s15, s14, 31
	v_lshl_add_u64 v[2:3], v[2:3], 0, s[8:9]
	s_lshl_b64 s[8:9], s[14:15], 3
	s_waitcnt lgkmcnt(0)
	v_lshl_add_u64 v[4:5], v[4:5], 4, s[10:11]
	s_lshl_b64 s[10:11], s[14:15], 4
	s_mov_b64 s[16:17], 0
	s_movk_i32 s15, 0x7fff
	s_mov_b32 s18, 0xfffff
	v_mov_b32_e32 v7, 1
	v_mov_b32_e32 v9, v6
	s_cmpk_lg_i32 s39, 0x100
	s_cbranch_scc1 .LBB0_28
	v_mov_b64_e32 v[70:71], v[4:5]
	global_load_dwordx4 v[80:83], v[70:71], off
	v_lshl_add_u64 v[70:71], v[70:71], 0, s[10:11]
	global_load_dwordx4 v[84:87], v[70:71], off
	v_lshl_add_u64 v[70:71], v[70:71], 0, s[10:11]
	global_load_dwordx4 v[88:91], v[70:71], off
	v_lshl_add_u64 v[70:71], v[70:71], 0, s[10:11]
	global_load_dwordx4 v[92:95], v[70:71], off
	v_lshl_add_u64 v[70:71], v[70:71], 0, s[10:11]
	global_load_dwordx4 v[96:99], v[70:71], off
	v_lshl_add_u64 v[70:71], v[70:71], 0, s[10:11]
	global_load_dwordx4 v[100:103], v[70:71], off
	v_lshl_add_u64 v[70:71], v[70:71], 0, s[10:11]
	global_load_dwordx4 v[104:107], v[70:71], off
	v_lshl_add_u64 v[70:71], v[70:71], 0, s[10:11]
	global_load_dwordx4 v[108:111], v[70:71], off
	v_mov_b64_e32 v[72:73], v[2:3]
	s_waitcnt vmcnt(7)
	v_cvt_pk_bf16_f32 v10, v80, v81
	v_cvt_pk_bf16_f32 v11, v82, v83
	global_store_dwordx2 v[72:73], v[10:11], off
	v_lshl_add_u64 v[72:73], v[72:73], 0, s[8:9]
	s_waitcnt vmcnt(7)
	v_cvt_pk_bf16_f32 v10, v84, v85
	v_cvt_pk_bf16_f32 v11, v86, v87
	global_store_dwordx2 v[72:73], v[10:11], off
	v_lshl_add_u64 v[72:73], v[72:73], 0, s[8:9]
	s_waitcnt vmcnt(7)
	v_cvt_pk_bf16_f32 v10, v88, v89
	v_cvt_pk_bf16_f32 v11, v90, v91
	global_store_dwordx2 v[72:73], v[10:11], off
	v_lshl_add_u64 v[72:73], v[72:73], 0, s[8:9]
	s_waitcnt vmcnt(7)
	v_cvt_pk_bf16_f32 v10, v92, v93
	v_cvt_pk_bf16_f32 v11, v94, v95
	global_store_dwordx2 v[72:73], v[10:11], off
	v_lshl_add_u64 v[72:73], v[72:73], 0, s[8:9]
	s_waitcnt vmcnt(7)
	v_cvt_pk_bf16_f32 v10, v96, v97
	v_cvt_pk_bf16_f32 v11, v98, v99
	global_store_dwordx2 v[72:73], v[10:11], off
	v_lshl_add_u64 v[72:73], v[72:73], 0, s[8:9]
	s_waitcnt vmcnt(7)
	v_cvt_pk_bf16_f32 v10, v100, v101
	v_cvt_pk_bf16_f32 v11, v102, v103
	global_store_dwordx2 v[72:73], v[10:11], off
	v_lshl_add_u64 v[72:73], v[72:73], 0, s[8:9]
	s_waitcnt vmcnt(7)
	v_cvt_pk_bf16_f32 v10, v104, v105
	v_cvt_pk_bf16_f32 v11, v106, v107
	global_store_dwordx2 v[72:73], v[10:11], off
	v_lshl_add_u64 v[72:73], v[72:73], 0, s[8:9]
	s_waitcnt vmcnt(7)
	v_cvt_pk_bf16_f32 v10, v108, v109
	v_cvt_pk_bf16_f32 v11, v110, v111
	global_store_dwordx2 v[72:73], v[10:11], off
	s_branch .LBB0_29
